# strategy 4, role-aware: in sample-group items the computing waves 0-3 get priority 1 and the loader waves 4-7 priority 0 (otherwise v025)
# baseline (speedup 1.0000x reference)
; __device__ __forceinline__ void attn_item(const P& p, Frame& F, const bool is_s, const int b, const int g, const int c) {
;     ...
;             const bool loader = is_s && tid >= 256;
; template <int LO, int HI> __global__ void __launch_bounds__(NTHR, 2) mega(P p) {
;     ...
;               const bool is_s = ia < 64; const int kk = is_s ? ia : ia - 64;
.LBB0_1872:
	s_sub_i32 s2, s10, 64
	s_cmp_lt_i32 s10, 64
	s_cselect_b64 s[0:1], -1, 0
	s_and_b64 s[0:1], s[0:1], exec
	s_cselect_b32 s5, s10, s2
	s_ashr_i32 s2, s5, 4
	s_sub_i32 s3, 31, s2
	s_cmp_lt_i32 s10, 64
	s_cselect_b64 s[8:9], -1, 0
	s_cbranch_scc0 .Lprio_smp_done
	s_setprio 0
	v_readfirstlane_b32 s0, v0
	s_nop 3
	s_bitcmp1_b32 s0, 8
	s_cbranch_scc1 .Lprio_smp_done
	s_setprio 1
